# attention loop: hipcc wave-uniform rescale test trimmed (v_cndmask+v_cmp_ne removed, s_or_b64 SCC feeds the branch), on top of v51
# baseline (speedup 1.0000x reference)
.LBB0_466:
	v_max3_f32 v33, v96, v97, v80
	v_max3_f32 v34, v98, v99, v81
	s_mov_b32 s6, 0x40c00000
	v_max3_f32 v33, v33, v82, v83
	v_max3_f32 v34, v34, v102, v103
	v_lshl_add_u64 v[252:253], v[216:217], 0, s[66:67]
	global_load_dwordx4 v[164:167], v[252:253], off
	s_nop 0
	v_max3_f32 v33, v33, v100, v101
	v_max3_f32 v34, v34, v86, v87
	s_nop 0
	v_max3_f32 v33, v33, v84, v85
	v_max3_f32 v34, v34, v106, v107
	s_nop 0
	v_max3_f32 v33, v33, v104, v105
	v_max3_f32 v34, v34, v90, v91
	s_nop 0
	v_max3_f32 v33, v33, v88, v89
	v_max3_f32 v34, v34, v110, v111
	s_nop 0
	v_max3_f32 v33, v33, v108, v109
	v_max3_f32 v34, v34, v94, v95
	s_nop 0
	v_max3_f32 v33, v33, v92, v93
	v_max_f32_e32 v34, v34, v34
	v_max_f32_e32 v33, v33, v33
	v_max_f32_e32 v33, v33, v34
	v_mov_b32_e32 v34, v33
	s_nop 1
	v_permlane32_swap_b32_e32 v33, v34
	v_max_f32_e32 v34, v34, v34
	v_max_f32_e32 v33, v33, v33
	v_max_f32_e32 v33, v33, v34
	v_sub_f32_e32 v33, v33, v214
	v_cmp_lt_f32_e32 vcc, s6, v33
	s_or_b64 s[6:7], s[40:41], vcc
	s_cbranch_scc0 .LBB0_468
	v_max_f32_e32 v34, v33, v33
	v_max_f32_e32 v34, 0, v34
	v_cndmask_b32_e64 v33, v34, v33, s[40:41]
	v_exp_f32_e64 v34, -v33
	v_add_f32_e32 v214, v214, v33
	v_cndmask_b32_e64 v34, v34, 1.0, s[40:41]
	v_pk_mul_f32 v[78:79], v[78:79], v[34:35] op_sel_hi:[1,0]
	v_pk_mul_f32 v[76:77], v[76:77], v[34:35] op_sel_hi:[1,0]
	v_pk_mul_f32 v[74:75], v[74:75], v[34:35] op_sel_hi:[1,0]
	v_pk_mul_f32 v[72:73], v[72:73], v[34:35] op_sel_hi:[1,0]
	v_pk_mul_f32 v[70:71], v[70:71], v[34:35] op_sel_hi:[1,0]
	v_pk_mul_f32 v[68:69], v[68:69], v[34:35] op_sel_hi:[1,0]
	v_pk_mul_f32 v[66:67], v[66:67], v[34:35] op_sel_hi:[1,0]
	v_pk_mul_f32 v[64:65], v[64:65], v[34:35] op_sel_hi:[1,0]
	v_pk_mul_f32 v[62:63], v[62:63], v[34:35] op_sel_hi:[1,0]
	v_pk_mul_f32 v[60:61], v[60:61], v[34:35] op_sel_hi:[1,0]
	v_pk_mul_f32 v[58:59], v[58:59], v[34:35] op_sel_hi:[1,0]
	v_pk_mul_f32 v[56:57], v[56:57], v[34:35] op_sel_hi:[1,0]
	v_pk_mul_f32 v[54:55], v[54:55], v[34:35] op_sel_hi:[1,0]
	v_pk_mul_f32 v[52:53], v[52:53], v[34:35] op_sel_hi:[1,0]
	v_pk_mul_f32 v[50:51], v[50:51], v[34:35] op_sel_hi:[1,0]
	v_pk_mul_f32 v[48:49], v[48:49], v[34:35] op_sel_hi:[1,0]
	v_pk_mul_f32 v[30:31], v[30:31], v[34:35] op_sel_hi:[1,0]
	v_pk_mul_f32 v[28:29], v[28:29], v[34:35] op_sel_hi:[1,0]
	v_pk_mul_f32 v[26:27], v[26:27], v[34:35] op_sel_hi:[1,0]
	v_pk_mul_f32 v[24:25], v[24:25], v[34:35] op_sel_hi:[1,0]
	v_pk_mul_f32 v[22:23], v[22:23], v[34:35] op_sel_hi:[1,0]
	v_pk_mul_f32 v[20:21], v[20:21], v[34:35] op_sel_hi:[1,0]
	v_pk_mul_f32 v[18:19], v[18:19], v[34:35] op_sel_hi:[1,0]
	v_pk_mul_f32 v[16:17], v[16:17], v[34:35] op_sel_hi:[1,0]
	v_pk_mul_f32 v[14:15], v[14:15], v[34:35] op_sel_hi:[1,0]
	v_pk_mul_f32 v[12:13], v[12:13], v[34:35] op_sel_hi:[1,0]
	v_pk_mul_f32 v[10:11], v[10:11], v[34:35] op_sel_hi:[1,0]
	v_pk_mul_f32 v[8:9], v[8:9], v[34:35] op_sel_hi:[1,0]
	v_pk_mul_f32 v[6:7], v[6:7], v[34:35] op_sel_hi:[1,0]
	v_pk_mul_f32 v[4:5], v[4:5], v[34:35] op_sel_hi:[1,0]
	v_pk_mul_f32 v[2:3], v[2:3], v[34:35] op_sel_hi:[1,0]
	v_pk_mul_f32 v[0:1], v[0:1], v[34:35] op_sel_hi:[1,0]
	v_mul_f32_e32 v250, v250, v34
	s_mov_b64 s[40:41], 0
